# S5 epilogue: all rows' x1 residual loads issued at the start (free registers) instead of two rows ahead
# baseline (speedup 1.0000x reference)
.LBB0_1111:
	v_lshl_add_u32 v146, s48, 8, v148
	v_lshl_or_b32 v142, s47, 8, v149
	v_ashrrev_i32_e32 v143, 31, v142
	v_or_b32_e32 v184, 32, v146
	v_lshlrev_b64 v[144:145], 1, v[142:143]
	v_ashrrev_i32_e32 v147, 31, v146
	v_or_b32_e32 v176, 16, v146
	v_ashrrev_i32_e32 v185, 31, v184
	v_lshl_add_u64 v[164:165], s[12:13], 0, v[144:145]
	v_lshlrev_b64 v[156:157], 11, v[146:147]
	v_ashrrev_i32_e32 v177, 31, v176
	v_lshlrev_b64 v[168:169], 11, v[184:185]
	v_lshl_add_u64 v[160:161], v[164:165], 0, v[156:157]
	v_lshlrev_b64 v[166:167], 11, v[176:177]
	v_lshl_add_u64 v[172:173], s[12:13], 0, v[168:169]
	v_mov_b64_e32 v[236:237], v[160:161]
	global_load_dwordx4 v[156:159], v[160:161], off nt
	s_nop 0
	global_load_dwordx4 v[160:163], v[160:161], off offset:256 nt
	v_lshl_add_u64 v[170:171], v[164:165], 0, v[166:167]
	v_lshl_add_u64 v[180:181], v[172:173], 0, v[144:145]
	global_load_dwordx4 v[164:167], v[170:171], off nt
	s_nop 0
	global_load_dwordx4 v[168:171], v[170:171], off offset:256 nt
	s_nop 0
	global_load_dwordx4 v[172:175], v[180:181], off nt
	s_nop 0
	global_load_dwordx4 v[180:183], v[180:181], off offset:256 nt
	s_mov_b64 s[98:99], 0x18000
	v_lshl_add_u64 v[238:239], v[236:237], 0, s[98:99]
	global_load_dwordx4 v[196:199], v[238:239], off nt
	global_load_dwordx4 v[200:203], v[238:239], off offset:256 nt
	s_mov_b64 s[98:99], 0x40000
	v_lshl_add_u64 v[238:239], v[236:237], 0, s[98:99]
	global_load_dwordx4 v[204:207], v[238:239], off nt
	global_load_dwordx4 v[208:211], v[238:239], off offset:256 nt
	s_mov_b64 s[98:99], 0x48000
	v_lshl_add_u64 v[238:239], v[236:237], 0, s[98:99]
	global_load_dwordx4 v[212:215], v[238:239], off nt
	global_load_dwordx4 v[216:219], v[238:239], off offset:256 nt
	s_mov_b64 s[98:99], 0x50000
	v_lshl_add_u64 v[238:239], v[236:237], 0, s[98:99]
	global_load_dwordx4 v[220:223], v[238:239], off nt
	global_load_dwordx4 v[224:227], v[238:239], off offset:256 nt
	s_mov_b64 s[98:99], 0x58000
	v_lshl_add_u64 v[238:239], v[236:237], 0, s[98:99]
	global_load_dwordx4 v[228:231], v[238:239], off nt
	global_load_dwordx4 v[232:235], v[238:239], off offset:256 nt
	v_lshlrev_b64 v[186:187], 12, v[146:147]
	v_lshlrev_b64 v[142:143], 2, v[142:143]
	v_lshl_add_u64 v[186:187], s[8:9], 0, v[186:187]
	v_lshl_add_u64 v[186:187], v[186:187], 0, v[142:143]
	s_waitcnt vmcnt(10)
	v_lshlrev_b32_e32 v188, 16, v156
	v_and_b32_e32 v189, 0xffff0000, v156
	v_lshlrev_b32_e32 v156, 16, v157
	v_and_b32_e32 v157, 0xffff0000, v157
	v_lshlrev_b32_e32 v190, 16, v158
	v_and_b32_e32 v191, 0xffff0000, v158
	v_lshlrev_b32_e32 v158, 16, v159
	v_and_b32_e32 v159, 0xffff0000, v159
	v_lshlrev_b32_e32 v192, 16, v160
	v_and_b32_e32 v193, 0xffff0000, v160
	v_lshlrev_b32_e32 v160, 16, v161
	v_and_b32_e32 v161, 0xffff0000, v161
	v_lshlrev_b32_e32 v194, 16, v162
	v_and_b32_e32 v195, 0xffff0000, v162
	v_lshlrev_b32_e32 v162, 16, v163
	v_and_b32_e32 v163, 0xffff0000, v163
	v_pk_add_f32 v[128:129], v[128:129], v[156:157]
	v_pk_add_f32 v[126:127], v[126:127], v[188:189]
	v_pk_add_f32 v[124:125], v[124:125], v[158:159]
	v_pk_add_f32 v[122:123], v[122:123], v[190:191]
	v_pk_add_f32 v[120:121], v[120:121], v[160:161]
	v_pk_add_f32 v[118:119], v[118:119], v[192:193]
	v_pk_add_f32 v[116:117], v[116:117], v[162:163]
	v_pk_add_f32 v[114:115], v[114:115], v[194:195]
	global_store_dwordx4 v[186:187], v[126:129], off nt
	global_store_dwordx4 v[186:187], v[122:125], off offset:16 nt
	global_store_dwordx4 v[186:187], v[118:121], off offset:512 nt
	global_store_dwordx4 v[186:187], v[114:117], off offset:528 nt
	v_or_b32_e32 v122, 48, v146
	v_ashrrev_i32_e32 v123, 31, v122
	v_lshlrev_b64 v[114:115], 11, v[122:123]
	v_lshl_add_u64 v[114:115], s[12:13], 0, v[114:115]
	v_lshl_add_u64 v[118:119], v[114:115], 0, v[144:145]
	s_waitcnt vmcnt(12)
	v_mov_b64_e32 v[114:115], v[196:197]
	v_mov_b64_e32 v[116:117], v[198:199]
	s_nop 0
	v_mov_b64_e32 v[118:119], v[200:201]
	v_mov_b64_e32 v[120:121], v[202:203]
	v_lshlrev_b64 v[124:125], 12, v[176:177]
	v_lshl_add_u64 v[124:125], s[8:9], 0, v[124:125]
	v_lshlrev_b32_e32 v126, 16, v164
	v_and_b32_e32 v127, 0xffff0000, v164
	v_lshlrev_b32_e32 v128, 16, v165
	v_and_b32_e32 v129, 0xffff0000, v165
	v_lshlrev_b32_e32 v156, 16, v166
	v_and_b32_e32 v157, 0xffff0000, v166
	v_lshlrev_b32_e32 v158, 16, v167
	v_and_b32_e32 v159, 0xffff0000, v167
	v_lshl_add_u64 v[124:125], v[124:125], 0, v[142:143]
	v_pk_add_f32 v[112:113], v[112:113], v[128:129]
	v_pk_add_f32 v[110:111], v[110:111], v[126:127]
	v_pk_add_f32 v[108:109], v[108:109], v[158:159]
	v_pk_add_f32 v[106:107], v[106:107], v[156:157]
	global_store_dwordx4 v[124:125], v[110:113], off nt
	global_store_dwordx4 v[124:125], v[106:109], off offset:16 nt
	s_nop 0
	v_lshlrev_b32_e32 v110, 16, v170
	v_lshlrev_b32_e32 v106, 16, v168
	v_and_b32_e32 v107, 0xffff0000, v168
	v_lshlrev_b32_e32 v108, 16, v169
	v_and_b32_e32 v109, 0xffff0000, v169
	v_and_b32_e32 v111, 0xffff0000, v170
	v_lshlrev_b32_e32 v112, 16, v171
	v_and_b32_e32 v113, 0xffff0000, v171
	v_pk_add_f32 v[104:105], v[104:105], v[108:109]
	v_pk_add_f32 v[102:103], v[102:103], v[106:107]
	v_pk_add_f32 v[100:101], v[100:101], v[112:113]
	v_pk_add_f32 v[98:99], v[98:99], v[110:111]
	global_store_dwordx4 v[124:125], v[102:105], off offset:512 nt
	global_store_dwordx4 v[124:125], v[98:101], off offset:528 nt
	v_add_u32_e32 v106, 0x80, v146
	v_ashrrev_i32_e32 v107, 31, v106
	v_lshlrev_b64 v[98:99], 11, v[106:107]
	v_lshl_add_u64 v[98:99], s[12:13], 0, v[98:99]
	v_lshl_add_u64 v[102:103], v[98:99], 0, v[144:145]
	s_waitcnt vmcnt(14)
	v_mov_b64_e32 v[98:99], v[204:205]
	v_mov_b64_e32 v[100:101], v[206:207]
	s_nop 0
	v_mov_b64_e32 v[102:103], v[208:209]
	v_mov_b64_e32 v[104:105], v[210:211]
	v_lshlrev_b64 v[108:109], 12, v[184:185]
	v_lshl_add_u64 v[108:109], s[8:9], 0, v[108:109]
	v_lshlrev_b32_e32 v110, 16, v172
	v_and_b32_e32 v111, 0xffff0000, v172
	v_lshlrev_b32_e32 v112, 16, v173
	v_and_b32_e32 v113, 0xffff0000, v173
	v_lshlrev_b32_e32 v124, 16, v174
	v_and_b32_e32 v125, 0xffff0000, v174
	v_lshlrev_b32_e32 v126, 16, v175
	v_and_b32_e32 v127, 0xffff0000, v175
	v_lshl_add_u64 v[108:109], v[108:109], 0, v[142:143]
	v_pk_add_f32 v[96:97], v[96:97], v[112:113]
	v_pk_add_f32 v[94:95], v[94:95], v[110:111]
	v_pk_add_f32 v[92:93], v[92:93], v[126:127]
	v_pk_add_f32 v[90:91], v[90:91], v[124:125]
	global_store_dwordx4 v[108:109], v[94:97], off nt
	global_store_dwordx4 v[108:109], v[90:93], off offset:16 nt
	s_nop 0
	v_lshlrev_b32_e32 v94, 16, v182
	v_lshlrev_b32_e32 v90, 16, v180
	v_and_b32_e32 v91, 0xffff0000, v180
	v_lshlrev_b32_e32 v92, 16, v181
	v_and_b32_e32 v93, 0xffff0000, v181
	v_and_b32_e32 v95, 0xffff0000, v182
	v_lshlrev_b32_e32 v96, 16, v183
	v_and_b32_e32 v97, 0xffff0000, v183
	v_pk_add_f32 v[88:89], v[88:89], v[92:93]
	v_pk_add_f32 v[86:87], v[86:87], v[90:91]
	v_pk_add_f32 v[84:85], v[84:85], v[96:97]
	v_pk_add_f32 v[82:83], v[82:83], v[94:95]
	global_store_dwordx4 v[108:109], v[86:89], off offset:512 nt
	global_store_dwordx4 v[108:109], v[82:85], off offset:528 nt
	v_add_u32_e32 v90, 0x90, v146
	v_ashrrev_i32_e32 v91, 31, v90
	v_lshlrev_b64 v[82:83], 11, v[90:91]
	v_lshl_add_u64 v[82:83], s[12:13], 0, v[82:83]
	v_lshl_add_u64 v[86:87], v[82:83], 0, v[144:145]
	s_waitcnt vmcnt(16)
	v_mov_b64_e32 v[82:83], v[212:213]
	v_mov_b64_e32 v[84:85], v[214:215]
	s_nop 0
	v_mov_b64_e32 v[86:87], v[216:217]
	v_mov_b64_e32 v[88:89], v[218:219]
	v_lshlrev_b64 v[92:93], 12, v[122:123]
	v_lshl_add_u64 v[92:93], s[8:9], 0, v[92:93]
	s_nop 0
	v_lshlrev_b32_e32 v94, 16, v114
	v_and_b32_e32 v95, 0xffff0000, v114
	v_lshlrev_b32_e32 v96, 16, v115
	v_and_b32_e32 v97, 0xffff0000, v115
	v_lshlrev_b32_e32 v108, 16, v116
	v_and_b32_e32 v109, 0xffff0000, v116
	v_lshlrev_b32_e32 v110, 16, v117
	v_and_b32_e32 v111, 0xffff0000, v117
	v_lshl_add_u64 v[92:93], v[92:93], 0, v[142:143]
	v_pk_add_f32 v[80:81], v[80:81], v[96:97]
	v_pk_add_f32 v[78:79], v[78:79], v[94:95]
	v_pk_add_f32 v[76:77], v[76:77], v[110:111]
	v_pk_add_f32 v[74:75], v[74:75], v[108:109]
	global_store_dwordx4 v[92:93], v[78:81], off nt
	global_store_dwordx4 v[92:93], v[74:77], off offset:16 nt
	s_nop 0
	v_lshlrev_b32_e32 v78, 16, v120
	v_lshlrev_b32_e32 v74, 16, v118
	v_and_b32_e32 v75, 0xffff0000, v118
	v_lshlrev_b32_e32 v76, 16, v119
	v_and_b32_e32 v77, 0xffff0000, v119
	v_and_b32_e32 v79, 0xffff0000, v120
	v_lshlrev_b32_e32 v80, 16, v121
	v_and_b32_e32 v81, 0xffff0000, v121
	v_pk_add_f32 v[72:73], v[72:73], v[76:77]
	v_pk_add_f32 v[70:71], v[70:71], v[74:75]
	v_pk_add_f32 v[68:69], v[68:69], v[80:81]
	v_pk_add_f32 v[66:67], v[66:67], v[78:79]
	global_store_dwordx4 v[92:93], v[70:73], off offset:512 nt
	global_store_dwordx4 v[92:93], v[66:69], off offset:528 nt
	v_add_u32_e32 v74, 0xa0, v146
	v_ashrrev_i32_e32 v75, 31, v74
	v_lshlrev_b64 v[66:67], 11, v[74:75]
	v_lshl_add_u64 v[66:67], s[12:13], 0, v[66:67]
	v_lshl_add_u64 v[70:71], v[66:67], 0, v[144:145]
	s_waitcnt vmcnt(18)
	v_mov_b64_e32 v[66:67], v[220:221]
	v_mov_b64_e32 v[68:69], v[222:223]
	s_nop 0
	v_mov_b64_e32 v[70:71], v[224:225]
	v_mov_b64_e32 v[72:73], v[226:227]
	v_lshlrev_b64 v[76:77], 12, v[106:107]
	v_lshl_add_u64 v[76:77], s[8:9], 0, v[76:77]
	s_nop 0
	v_lshlrev_b32_e32 v78, 16, v98
	v_and_b32_e32 v79, 0xffff0000, v98
	v_lshlrev_b32_e32 v80, 16, v99
	v_and_b32_e32 v81, 0xffff0000, v99
	v_lshlrev_b32_e32 v92, 16, v100
	v_and_b32_e32 v93, 0xffff0000, v100
	v_lshlrev_b32_e32 v94, 16, v101
	v_and_b32_e32 v95, 0xffff0000, v101
	v_lshl_add_u64 v[76:77], v[76:77], 0, v[142:143]
	v_pk_add_f32 v[64:65], v[64:65], v[80:81]
	v_pk_add_f32 v[62:63], v[62:63], v[78:79]
	v_pk_add_f32 v[60:61], v[60:61], v[94:95]
	v_pk_add_f32 v[58:59], v[58:59], v[92:93]
	global_store_dwordx4 v[76:77], v[62:65], off nt
	global_store_dwordx4 v[76:77], v[58:61], off offset:16 nt
	s_nop 0
	v_lshlrev_b32_e32 v62, 16, v104
	v_lshlrev_b32_e32 v58, 16, v102
	v_and_b32_e32 v59, 0xffff0000, v102
	v_lshlrev_b32_e32 v60, 16, v103
	v_and_b32_e32 v61, 0xffff0000, v103
	v_and_b32_e32 v63, 0xffff0000, v104
	v_lshlrev_b32_e32 v64, 16, v105
	v_and_b32_e32 v65, 0xffff0000, v105
	v_pk_add_f32 v[56:57], v[56:57], v[60:61]
	v_pk_add_f32 v[54:55], v[54:55], v[58:59]
	v_pk_add_f32 v[52:53], v[52:53], v[64:65]
	v_pk_add_f32 v[50:51], v[50:51], v[62:63]
	global_store_dwordx4 v[76:77], v[54:57], off offset:512 nt
	global_store_dwordx4 v[76:77], v[50:53], off offset:528 nt
	v_add_u32_e32 v58, 0xb0, v146
	v_ashrrev_i32_e32 v59, 31, v58
	v_lshlrev_b64 v[50:51], 11, v[58:59]
	v_lshl_add_u64 v[50:51], s[12:13], 0, v[50:51]
	v_lshl_add_u64 v[60:61], v[50:51], 0, v[144:145]
	s_waitcnt vmcnt(20)
	v_mov_b64_e32 v[50:51], v[228:229]
	v_mov_b64_e32 v[52:53], v[230:231]
	v_mov_b64_e32 v[54:55], v[232:233]
	v_mov_b64_e32 v[56:57], v[234:235]
	v_lshlrev_b64 v[60:61], 12, v[90:91]
	v_lshl_add_u64 v[60:61], s[8:9], 0, v[60:61]
	s_nop 0
	v_lshlrev_b32_e32 v62, 16, v82
	v_and_b32_e32 v63, 0xffff0000, v82
	v_lshlrev_b32_e32 v64, 16, v83
	v_and_b32_e32 v65, 0xffff0000, v83
	v_lshlrev_b32_e32 v76, 16, v84
	v_and_b32_e32 v77, 0xffff0000, v84
	v_lshlrev_b32_e32 v78, 16, v85
	v_and_b32_e32 v79, 0xffff0000, v85
	v_lshl_add_u64 v[60:61], v[60:61], 0, v[142:143]
	v_pk_add_f32 v[48:49], v[48:49], v[64:65]
	v_pk_add_f32 v[46:47], v[46:47], v[62:63]
	v_pk_add_f32 v[44:45], v[44:45], v[78:79]
	v_pk_add_f32 v[42:43], v[42:43], v[76:77]
	global_store_dwordx4 v[60:61], v[46:49], off nt
	global_store_dwordx4 v[60:61], v[42:45], off offset:16 nt
	s_nop 0
	v_lshlrev_b32_e32 v46, 16, v88
	v_lshlrev_b32_e32 v42, 16, v86
	v_and_b32_e32 v43, 0xffff0000, v86
	v_lshlrev_b32_e32 v44, 16, v87
	v_and_b32_e32 v45, 0xffff0000, v87
	v_and_b32_e32 v47, 0xffff0000, v88
	v_lshlrev_b32_e32 v48, 16, v89
	v_and_b32_e32 v49, 0xffff0000, v89
	v_pk_add_f32 v[40:41], v[40:41], v[44:45]
	v_pk_add_f32 v[38:39], v[38:39], v[42:43]
	v_pk_add_f32 v[32:33], v[32:33], v[48:49]
	v_pk_add_f32 v[30:31], v[30:31], v[46:47]
	global_store_dwordx4 v[60:61], v[38:41], off offset:512 nt
	global_store_dwordx4 v[60:61], v[30:33], off offset:528 nt
	s_nop 1
	v_lshlrev_b64 v[30:31], 12, v[74:75]
	v_lshl_add_u64 v[30:31], s[8:9], 0, v[30:31]
	v_lshl_add_u64 v[38:39], v[30:31], 0, v[142:143]
	s_nop 0
	v_lshlrev_b32_e32 v30, 16, v66
	v_and_b32_e32 v31, 0xffff0000, v66
	v_lshlrev_b32_e32 v32, 16, v67
	v_and_b32_e32 v33, 0xffff0000, v67
	v_lshlrev_b32_e32 v40, 16, v68
	v_and_b32_e32 v41, 0xffff0000, v68
	v_lshlrev_b32_e32 v42, 16, v69
	v_and_b32_e32 v43, 0xffff0000, v69
	v_pk_add_f32 v[32:33], v[36:37], v[32:33]
	v_pk_add_f32 v[30:31], v[34:35], v[30:31]
	v_pk_add_f32 v[28:29], v[28:29], v[42:43]
	v_pk_add_f32 v[26:27], v[26:27], v[40:41]
	global_store_dwordx4 v[38:39], v[30:33], off nt
	global_store_dwordx4 v[38:39], v[26:29], off offset:16 nt
	s_nop 0
	v_lshlrev_b32_e32 v30, 16, v72
	v_lshlrev_b32_e32 v26, 16, v70
	v_and_b32_e32 v27, 0xffff0000, v70
	v_lshlrev_b32_e32 v28, 16, v71
	v_and_b32_e32 v29, 0xffff0000, v71
	v_and_b32_e32 v31, 0xffff0000, v72
	v_lshlrev_b32_e32 v32, 16, v73
	v_and_b32_e32 v33, 0xffff0000, v73
	v_pk_add_f32 v[24:25], v[24:25], v[28:29]
	v_pk_add_f32 v[22:23], v[22:23], v[26:27]
	v_pk_add_f32 v[16:17], v[16:17], v[32:33]
	v_pk_add_f32 v[14:15], v[14:15], v[30:31]
	global_store_dwordx4 v[38:39], v[22:25], off offset:512 nt
	global_store_dwordx4 v[38:39], v[14:17], off offset:528 nt
	s_nop 1
	v_lshlrev_b64 v[14:15], 12, v[58:59]
	v_lshl_add_u64 v[14:15], s[8:9], 0, v[14:15]
	v_lshl_add_u64 v[22:23], v[14:15], 0, v[142:143]
	s_nop 0
	v_lshlrev_b32_e32 v14, 16, v50
	v_and_b32_e32 v15, 0xffff0000, v50
	v_lshlrev_b32_e32 v16, 16, v51
	v_and_b32_e32 v17, 0xffff0000, v51
	v_lshlrev_b32_e32 v24, 16, v52
	v_and_b32_e32 v25, 0xffff0000, v52
	v_lshlrev_b32_e32 v26, 16, v53
	v_and_b32_e32 v27, 0xffff0000, v53
	v_pk_add_f32 v[16:17], v[20:21], v[16:17]
	v_pk_add_f32 v[14:15], v[18:19], v[14:15]
	v_pk_add_f32 v[12:13], v[12:13], v[26:27]
	v_pk_add_f32 v[10:11], v[10:11], v[24:25]
	global_store_dwordx4 v[22:23], v[14:17], off nt
	global_store_dwordx4 v[22:23], v[10:13], off offset:16 nt
	s_nop 0
	v_lshlrev_b32_e32 v14, 16, v56
	v_lshlrev_b32_e32 v10, 16, v54
	v_and_b32_e32 v11, 0xffff0000, v54
	v_lshlrev_b32_e32 v12, 16, v55
	v_and_b32_e32 v13, 0xffff0000, v55
	v_and_b32_e32 v15, 0xffff0000, v56
	v_lshlrev_b32_e32 v16, 16, v57
	v_and_b32_e32 v17, 0xffff0000, v57
	v_pk_add_f32 v[8:9], v[8:9], v[12:13]
	v_pk_add_f32 v[6:7], v[6:7], v[10:11]
	v_pk_add_f32 v[4:5], v[4:5], v[16:17]
	v_pk_add_f32 v[2:3], v[2:3], v[14:15]
	global_store_dwordx4 v[22:23], v[6:9], off offset:512 nt
	global_store_dwordx4 v[22:23], v[2:5], off offset:528 nt
	s_and_b64 vcc, exec, s[6:7]
	s_mov_b64 s[6:7], -1
	s_cbranch_vccnz .LBB0_1104
	s_andn2_b64 vcc, exec, s[10:11]
	s_cbranch_vccnz .LBB0_1103
	s_barrier
	s_branch .LBB0_1103
